# diff-attention tile loop: second back-to-back s_barrier at the tile end (tighter wave alignment)
# speedup vs baseline: 1.0549x; 1.0022x over previous
.Ldl_join:
	v_cvt_pk_bf16_f32 v104, v112, v113
	v_cvt_pk_bf16_f32 v105, v114, v115
	v_cvt_pk_bf16_f32 v106, v116, v117
	v_cvt_pk_bf16_f32 v107, v118, v119
	v_cvt_pk_bf16_f32 v96, v176, v177
	v_cvt_pk_bf16_f32 v97, v178, v179
	v_cvt_pk_bf16_f32 v98, v180, v181
	v_cvt_pk_bf16_f32 v99, v182, v183
	v_cvt_pk_bf16_f32 v108, v120, v121
	v_cvt_pk_bf16_f32 v109, v122, v123
	v_cvt_pk_bf16_f32 v110, v124, v125
	v_cvt_pk_bf16_f32 v111, v126, v127
	v_cvt_pk_bf16_f32 v100, v184, v185
	v_cvt_pk_bf16_f32 v101, v186, v187
	v_cvt_pk_bf16_f32 v102, v188, v189
	v_cvt_pk_bf16_f32 v103, v190, v191
	s_mov_b64 s[6:7], -1
	v_pk_add_f32 v[112:113], v[114:115], v[112:113]
	v_pk_add_f32 v[114:115], v[178:179], v[176:177]
	v_pk_add_f32 v[112:113], v[116:117], v[112:113]
	v_pk_add_f32 v[114:115], v[180:181], v[114:115]
	v_pk_add_f32 v[112:113], v[118:119], v[112:113]
	v_pk_add_f32 v[114:115], v[182:183], v[114:115]
	v_pk_add_f32 v[112:113], v[120:121], v[112:113]
	v_pk_add_f32 v[114:115], v[184:185], v[114:115]
	s_add_i32 s46, s46, 1
	s_add_i32 s20, s45, 1
	v_pk_add_f32 v[112:113], v[122:123], v[112:113]
	v_pk_add_f32 v[114:115], v[186:187], v[114:115]
	s_cmp_lg_u32 s20, 3
	v_pk_add_f32 v[112:113], v[124:125], v[112:113]
	v_pk_add_f32 v[114:115], v[188:189], v[114:115]
	s_cselect_b32 s20, s20, 0
	s_add_u32 s16, s16, 0x80
	v_pk_add_f32 v[112:113], v[126:127], v[112:113]
	v_pk_add_f32 v[114:115], v[190:191], v[114:115]
	s_addc_u32 s17, s17, 0
	v_pk_add_f32 v[112:113], v[114:115], v[112:113]
	s_add_u32 s18, s18, 0x82000
	s_waitcnt lgkmcnt(0)
	s_barrier
	s_barrier
	v_add_f32_e32 v112, v112, v113
	s_addc_u32 s19, s19, 0
	v_add_f32_e32 v166, v166, v112
	s_cmpk_eq_i32 s46, 0x46
	s_cbranch_scc1 .LBB0_940
	s_mov_b32 s47, s3
	s_mov_b32 s3, s45
	s_mov_b32 s45, s20
	s_branch .LBB0_928
